# w2 + MLP down GEMM walks its tiles in reverse order (reads the most recently written rows of H first, while they are still in the Infinity Cache)
# baseline (speedup 1.0000x reference)
.LBB0_1222:
	v_readlane_b32 s0, v254, 0
	v_readlane_b32 s1, v254, 1
	v_readlane_b32 s2, v254, 4
	v_mbcnt_lo_u32_b32 v0, -1, 0
	v_mbcnt_hi_u32_b32 v0, -1, v0
	s_mov_b32 s19, s80
	v_readlane_b32 s2, v254, 5
	v_readlane_b32 s3, v254, 6
	s_waitcnt vmcnt(0)
	v_mov_b64_e32 v[2:3], s[0:1]
	s_load_dword s18, s[2:3], 0x0
	flat_load_dwordx4 v[2:5], v[2:3] offset:216
	v_readlane_b32 s0, v254, 22
	s_cmp_eq_u32 s0, 3
	s_mov_b64 s[0:1], 0x4200000
	s_waitcnt vmcnt(0) lgkmcnt(0)
	v_lshl_add_u64 v[198:199], v[4:5], 0, s[0:1]
	s_mov_b64 s[0:1], 0x8200000
	v_lshl_add_u64 v[200:201], v[4:5], 0, s[0:1]
	s_mov_b64 s[0:1], 0x12200000
	v_lshl_add_u64 v[202:203], v[4:5], 0, s[0:1]
	s_mov_b64 s[0:1], -1
	s_cbranch_scc1 .LBB0_1258
	v_mbcnt_lo_u32_b32 v0, -1, 0
	v_mbcnt_hi_u32_b32 v0, -1, v0
	s_cmpk_lt_i32 s19, 0x500
	v_add_u32_e32 v0, s81, v0
	s_cselect_b64 s[0:1], -1, 0
	s_cmpk_gt_i32 s19, 0x4ff
	v_readfirstlane_b32 s2, v0
	s_cbranch_scc1 .LBB0_1225
	s_ashr_i32 s3, s19, 31
	s_lshr_b32 s3, s3, 29
	s_add_i32 s3, s19, s3
	s_ashr_i32 s4, s3, 3
	s_and_b32 s3, s3, -8
	s_sub_i32 s3, s19, s3
	s_cmp_lt_i32 s3, 0
	s_movk_i32 s5, 0xa1
	s_cselect_b32 s5, s5, 0xa0
	s_mul_i32 s3, s3, s5
	s_add_i32 s3, s3, s4
	s_sub_i32 s3, 0x4ff, s3
	s_ashr_i32 s4, s3, 31
	s_lshr_b32 s4, s4, 26
	s_add_i32 s4, s3, s4
	s_ashr_i32 s5, s4, 5
	s_and_b32 s4, s4, 0xffe0
	s_sub_i32 s3, s3, s4
	s_bfe_i32 s4, s3, 0x80000
	s_bfe_u32 s4, s4, 0x3000c
	s_add_i32 s4, s3, s4
	s_bfe_i32 s6, s4, 0x80000
	s_and_b32 s4, s4, 0xfc
	s_sub_i32 s3, s3, s4
	s_lshl_b32 s5, s5, 2
	s_sext_i32_i16 s6, s6
	s_sext_i32_i8 s3, s3
	s_add_i32 s14, s5, s3
	s_ashr_i32 s12, s6, 2

.LBB0_1231:
	s_add_i32 s28, s28, 1
	s_mul_i32 s6, s28, s29
	s_mul_hi_u32 s7, s28, s18
	s_add_i32 s7, s7, s6
	s_mul_i32 s6, s28, s18
	s_add_u32 s16, s6, s19
	s_addc_u32 s17, s7, s30
	v_mov_b64_e32 v[136:137], 0x4ff
	v_cmp_gt_i64_e32 vcc, s[16:17], v[136:137]
	v_cmp_lt_i64_e64 s[6:7], s[16:17], v[242:243]
	s_cbranch_vccnz .LBB0_1233
	s_ashr_i32 s8, s16, 31
	s_lshr_b32 s8, s8, 29
	s_add_i32 s8, s16, s8
	s_ashr_i32 s9, s8, 3
	s_and_b32 s8, s8, -8
	s_sub_i32 s8, s16, s8
	s_cmp_lt_i32 s8, 0
	s_movk_i32 s10, 0xa1
	s_cselect_b32 s10, s10, 0xa0
	s_mul_i32 s8, s8, s10
	s_add_i32 s8, s8, s9
	s_sub_i32 s8, 0x4ff, s8
	s_ashr_i32 s9, s8, 31
	s_lshr_b32 s9, s9, 26
	s_add_i32 s9, s8, s9
	s_ashr_i32 s10, s9, 5
	s_lshl_b32 s10, s10, 2
	s_sub_i32 s11, 0xa0, s10
	s_min_i32 s11, s11, 4
	s_abs_i32 s13, s11
	v_cvt_f32_u32_e32 v0, s13
	s_sub_i32 s16, 0, s13
	s_andn2_b32 s9, s9, 31
	s_sub_i32 s9, s8, s9
	v_rcp_iflag_f32_e32 v0, v0
	s_abs_i32 s8, s9
	s_xor_b32 s15, s9, s11
	s_ashr_i32 s15, s15, 31
	v_mul_f32_e32 v0, 0x4f7ffffe, v0
	v_cvt_u32_f32_e32 v0, v0
	s_nop 0
	v_readfirstlane_b32 s17, v0
	s_mul_i32 s16, s16, s17
	s_mul_hi_u32 s16, s17, s16
	s_add_i32 s17, s17, s16
	s_mul_hi_u32 s16, s8, s17
	s_mul_i32 s17, s16, s13
	s_sub_i32 s8, s8, s17
	s_add_i32 s31, s16, 1
	s_sub_i32 s17, s8, s13
	s_cmp_ge_u32 s8, s13
	s_cselect_b32 s16, s31, s16
	s_cselect_b32 s8, s17, s8
	s_add_i32 s17, s16, 1
	s_cmp_ge_u32 s8, s13
	s_cselect_b32 s8, s17, s16
	s_xor_b32 s8, s8, s15
	s_sub_i32 s8, s8, s15
	s_mul_i32 s11, s8, s11
	s_sub_i32 s9, s9, s11
	s_add_i32 s10, s10, s9

.LBB0_1258:
	s_and_b64 vcc, exec, s[0:1]
	s_cbranch_vccz .LBB0_1275
	v_mbcnt_lo_u32_b32 v0, -1, 0
	v_mbcnt_hi_u32_b32 v0, -1, v0
	s_cmpk_gt_i32 s19, 0x4ff
	v_add_u32_e32 v0, s81, v0
	s_nop 0
	v_readfirstlane_b32 s3, v0
	s_cbranch_scc1 .LBB0_1275
	v_bfe_i32 v5, v0, 27, 1
	v_lshlrev_b32_e32 v4, 4, v0
	v_lshrrev_b32_e32 v5, 22, v5
	v_add_u32_e32 v5, v4, v5
	v_and_b32_e32 v5, 0xfffffc00, v5
	v_sub_u32_e32 v4, v4, v5
	v_lshrrev_b32_e32 v5, 4, v4
	v_ashrrev_i32_e32 v6, 31, v0
	v_bitop3_b32 v4, v5, v4, 32 bitop3:0x6c
	v_lshrrev_b32_e32 v6, 26, v6
	v_ashrrev_i32_e32 v5, 31, v4
	v_add_u32_e32 v6, v0, v6
	v_lshrrev_b32_e32 v5, 26, v5
	v_ashrrev_i32_e32 v141, 6, v6
	v_add_u32_e32 v5, v4, v5
	v_lshlrev_b32_e32 v6, 3, v141
	v_ashrrev_i32_e32 v140, 6, v5
	v_and_b32_e32 v6, -16, v6
	v_add_u32_e32 v6, v140, v6
	v_and_b32_e32 v7, 3, v140
	s_mov_b32 s0, 0x3ffe0
	s_ashr_i32 s15, s19, 31
	v_and_or_b32 v7, v6, s0, v7
	s_lshr_b32 s0, s15, 29
	s_add_i32 s0, s19, s0
	s_ashr_i32 s4, s3, 6
	s_ashr_i32 s1, s0, 3
	s_and_b32 s0, s0, -8
	s_ashr_i32 s5, s3, 8
	s_lshl_b32 s14, s4, 10
	s_sub_i32 s0, s19, s0
	s_cmp_lt_i32 s0, 0
	s_movk_i32 s2, 0xa1
	s_cselect_b32 s2, s2, 0xa0
	s_mul_i32 s0, s0, s2
	s_add_i32 s0, s0, s1
	s_sub_i32 s0, 0x4ff, s0
	s_ashr_i32 s1, s0, 31
	s_lshr_b32 s1, s1, 26
	s_add_i32 s1, s0, s1
	s_ashr_i32 s2, s1, 5
	s_and_b32 s1, s1, 0xffe0
	s_sub_i32 s0, s0, s1
	s_bfe_i32 s1, s0, 0x80000
	s_bfe_u32 s1, s1, 0x3000c
	s_add_i32 s1, s0, s1
	v_lshrrev_b32_e32 v8, 2, v6
	v_lshlrev_b32_e32 v9, 1, v6
	v_and_b32_e32 v5, 0xc0, v5
	s_lshl_b32 s6, s2, 2
	s_bfe_i32 s2, s1, 0x80000
	s_and_b32 s1, s1, 0xfc
	v_and_b32_e32 v8, 4, v8
	v_and_b32_e32 v9, 24, v9
	v_sub_u32_e32 v4, v4, v5
	s_sext_i32_i16 s2, s2
	s_sub_i32 s0, s0, s1
	v_or3_b32 v7, v7, v8, v9
	v_lshlrev_b32_e32 v8, 5, v141
	v_ashrrev_i16_sdwa v4, v241, sext(v4) dst_sel:DWORD dst_unused:UNUSED_PAD src0_sel:DWORD src1_sel:BYTE_0
	s_lshr_b32 s2, s2, 2
	s_sext_i32_i8 s0, s0
	v_and_b32_e32 v8, 32, v8
	v_bfe_i32 v142, v4, 0, 16
	s_add_i32 s10, s6, s0
	s_bfe_i64 s[6:7], s[2:3], 0x100000
	v_add_lshl_u32 v4, v8, v142, 1
	s_lshl_b64 s[6:7], s[6:7], 22
	v_lshl_add_u32 v192, v7, 14, v4
	v_lshl_add_u64 v[132:133], v[198:199], 0, s[6:7]
	v_mov_b32_e32 v193, v1
	s_add_i32 s16, s14, 0
	v_lshl_add_u64 v[134:135], v[132:133], 0, v[192:193]
	s_add_i32 m0, s16, 0x10000
	v_lshl_add_u32 v194, v6, 14, v4
	v_mov_b32 v124, 0
	v_mov_b32 v125, 0
	v_mov_b32 v126, 0
	v_mov_b32 v127, 0
	v_mov_b32 v128, 0
	v_mov_b32 v129, 0
	v_mov_b32 v130, 0
	v_mov_b32 v131, 0
	v_mov_b32 v112, 0
	v_mov_b32 v113, 0
	v_mov_b32 v114, 0
	v_mov_b32 v115, 0
	v_mov_b32 v108, 0
	v_mov_b32 v109, 0
	v_mov_b32 v110, 0
	v_mov_b32 v111, 0
	v_mov_b32 v96, 0
	v_mov_b32 v97, 0
	v_mov_b32 v98, 0
	v_mov_b32 v99, 0
	v_mov_b32 v92, 0
	v_mov_b32 v93, 0
	v_mov_b32 v94, 0
	v_mov_b32 v95, 0
	v_mov_b32 v80, 0
	v_mov_b32 v81, 0
	v_mov_b32 v82, 0
	v_mov_b32 v83, 0
	v_mov_b32 v76, 0
	v_mov_b32 v77, 0
	v_mov_b32 v78, 0
	v_mov_b32 v79, 0
	v_mov_b32 v120, 0
	v_mov_b32 v121, 0
	v_mov_b32 v122, 0
	v_mov_b32 v123, 0
	v_mov_b32 v116, 0
	v_mov_b32 v117, 0
	v_mov_b32 v118, 0
	v_mov_b32 v119, 0
	v_mov_b32 v104, 0
	v_mov_b32 v105, 0
	v_mov_b32 v106, 0
	v_mov_b32 v107, 0
	v_mov_b32 v100, 0
	v_mov_b32 v101, 0
	v_mov_b32 v102, 0
	v_mov_b32 v103, 0
	v_mov_b32 v88, 0
	v_mov_b32 v89, 0
	v_mov_b32 v90, 0
	v_mov_b32 v91, 0
	v_mov_b32 v84, 0
	v_mov_b32 v85, 0
	v_mov_b32 v86, 0
	v_mov_b32 v87, 0
	v_mov_b32 v72, 0
	v_mov_b32 v73, 0
	v_mov_b32 v74, 0
	v_mov_b32 v75, 0
	v_mov_b32 v68, 0
	v_mov_b32 v69, 0
	v_mov_b32 v70, 0
	v_mov_b32 v71, 0
	v_mov_b32 v64, 0
	v_mov_b32 v65, 0
	v_mov_b32 v66, 0
	v_mov_b32 v67, 0
	v_mov_b32 v60, 0
	v_mov_b32 v61, 0
	v_mov_b32 v62, 0
	v_mov_b32 v63, 0
	v_mov_b32 v48, 0
	v_mov_b32 v49, 0
	v_mov_b32 v50, 0
	v_mov_b32 v51, 0
	v_mov_b32 v44, 0
	v_mov_b32 v45, 0
	v_mov_b32 v46, 0
	v_mov_b32 v47, 0
	v_mov_b32 v32, 0
	v_mov_b32 v33, 0
	v_mov_b32 v34, 0
	v_mov_b32 v35, 0
	v_mov_b32 v28, 0
	v_mov_b32 v29, 0
	v_mov_b32 v30, 0
	v_mov_b32 v31, 0
	v_mov_b32 v16, 0
	v_mov_b32 v17, 0
	v_mov_b32 v18, 0
	v_mov_b32 v19, 0
	v_mov_b32 v12, 0
	v_mov_b32 v13, 0
	v_mov_b32 v14, 0
	v_mov_b32 v15, 0
	v_mov_b32 v56, 0
	v_mov_b32 v57, 0
	v_mov_b32 v58, 0
	v_mov_b32 v59, 0
	v_mov_b32 v52, 0
	v_mov_b32 v53, 0
	v_mov_b32 v54, 0
	v_mov_b32 v55, 0
	v_mov_b32 v40, 0
	v_mov_b32 v41, 0
	v_mov_b32 v42, 0
	v_mov_b32 v43, 0
	v_mov_b32 v36, 0
	v_mov_b32 v37, 0
	v_mov_b32 v38, 0
	v_mov_b32 v39, 0
	v_mov_b32 v24, 0
	v_mov_b32 v25, 0
	v_mov_b32 v26, 0
	v_mov_b32 v27, 0
	v_mov_b32 v20, 0
	v_mov_b32 v21, 0
	v_mov_b32 v22, 0
	v_mov_b32 v23, 0
	v_mov_b32 v8, 0
	v_mov_b32 v9, 0
	v_mov_b32 v10, 0
	v_mov_b32 v11, 0
	v_mov_b32 v4, 0
	v_mov_b32 v5, 0
	v_mov_b32 v6, 0
	v_mov_b32 v7, 0
	s_ashr_i32 s11, s10, 31
	global_load_lds_dwordx4 v[134:135], off
	v_lshl_add_u64 v[136:137], v[134:135], 0, s[84:85]
	s_add_i32 m0, s16, 0x12000
	s_lshl_b64 s[0:1], s[10:11], 22
	global_load_lds_dwordx4 v[136:137], off
	v_lshl_add_u64 v[136:137], v[134:135], 0, s[50:51]
	s_add_i32 m0, s16, 0x14000
	v_lshl_add_u64 v[138:139], v[202:203], 0, s[0:1]
	global_load_lds_dwordx4 v[136:137], off
	v_lshl_add_u64 v[136:137], v[134:135], 0, s[94:95]
	s_add_i32 m0, s16, 0x16000
	v_mov_b32_e32 v195, v1
	global_load_lds_dwordx4 v[136:137], off
	v_lshl_add_u64 v[136:137], v[138:139], 0, v[194:195]
	s_mov_b32 m0, s16
	s_add_i32 s17, s16, 0x2000
	global_load_lds_dwordx4 v[136:137], off
	v_lshl_add_u64 v[144:145], v[136:137], 0, s[84:85]
	s_mov_b32 m0, s17
	s_add_i32 s20, s16, 0x4000
	global_load_lds_dwordx4 v[144:145], off
	v_lshl_add_u64 v[144:145], v[136:137], 0, s[50:51]
	s_mov_b32 m0, s20
	s_add_i32 s21, s16, 0x6000
	global_load_lds_dwordx4 v[144:145], off
	v_lshl_add_u64 v[144:145], v[136:137], 0, s[94:95]
	s_mov_b32 m0, s21
	s_cmp_eq_u32 s5, 1
	global_load_lds_dwordx4 v[144:145], off
	s_cselect_b64 s[0:1], -1, 0
	s_cmp_lg_u32 s5, 1
	s_cbranch_scc1 .LBB0_1262
	s_barrier

.LBB0_1265:
	s_add_i32 s25, s25, 1
	s_mul_i32 s4, s25, s24
	s_mul_hi_u32 s5, s25, s18
	s_add_i32 s5, s5, s4
	s_mul_i32 s4, s25, s18
	s_add_u32 s12, s4, s19
	s_addc_u32 s13, s5, s15
	v_mov_b64_e32 v[134:135], 0x4ff
	v_cmp_gt_i64_e32 vcc, s[12:13], v[134:135]
	v_mov_b64_e32 v[252:253], 0x500
	v_cmp_lt_i64_e64 s[4:5], s[12:13], v[242:243]
	s_cbranch_vccnz .LBB0_1267
	s_ashr_i32 s6, s12, 31
	s_lshr_b32 s6, s6, 29
	s_add_i32 s6, s12, s6
	s_ashr_i32 s7, s6, 3
	s_and_b32 s6, s6, -8
	s_sub_i32 s6, s12, s6
	s_cmp_lt_i32 s6, 0
	s_movk_i32 s8, 0xa1
	s_cselect_b32 s8, s8, 0xa0
	s_mul_i32 s6, s6, s8
	s_add_i32 s6, s6, s7
	s_sub_i32 s6, 0x4ff, s6
	s_ashr_i32 s7, s6, 31
	s_lshr_b32 s7, s7, 26
	s_add_i32 s7, s6, s7
	s_ashr_i32 s8, s7, 5
	s_lshl_b32 s8, s8, 2
	s_sub_i32 s9, 0xa0, s8
	s_min_i32 s9, s9, 4
	s_abs_i32 s12, s9
	v_cvt_f32_u32_e32 v0, s12
	s_sub_i32 s26, 0, s12
	s_andn2_b32 s7, s7, 31
	s_sub_i32 s7, s6, s7
	v_rcp_iflag_f32_e32 v0, v0
	s_abs_i32 s6, s7
	s_xor_b32 s13, s7, s9
	s_ashr_i32 s13, s13, 31
	v_mul_f32_e32 v0, 0x4f7ffffe, v0
	v_cvt_u32_f32_e32 v0, v0
	s_nop 0
	v_readfirstlane_b32 s27, v0
	s_mul_i32 s26, s26, s27
	s_mul_hi_u32 s26, s27, s26
	s_add_i32 s27, s27, s26
	s_mul_hi_u32 s26, s6, s27
	s_mul_i32 s27, s26, s12
	s_sub_i32 s6, s6, s27
	s_add_i32 s28, s26, 1
	s_sub_i32 s27, s6, s12
	s_cmp_ge_u32 s6, s12
	s_cselect_b32 s26, s28, s26
	s_cselect_b32 s6, s27, s6
	s_add_i32 s27, s26, 1
	s_cmp_ge_u32 s6, s12
	s_cselect_b32 s6, s27, s26
	s_xor_b32 s6, s6, s13
	s_sub_i32 s6, s6, s13
	s_mul_i32 s9, s6, s9
	s_sub_i32 s7, s7, s9
	s_add_i32 s8, s8, s7
